# attention main loop: s_setprio 1/0 around the QK^T and P.V MFMA clusters
# baseline (speedup 1.0000x reference)
.LBB0_507:
	s_add_i32 s8, s25, 1
	s_bitcmp1_b32 s8, 0
	s_cselect_b32 s33, 0x2400, 0
	v_add_u32_e32 v153, s33, v145
	ds_read_b128 v[64:67], v153
	ds_read_b128 v[136:139], v153 offset:32
	ds_read_b128 v[140:143], v153 offset:4608
	ds_read_b128 v[182:185], v153 offset:4640
	s_mov_b32 s59, s38
	s_setprio 1
	s_waitcnt lgkmcnt(3)
	v_mfma_f32_32x32x16_bf16 v[48:63], v[64:67], v[80:83], v[0:15]
	s_waitcnt lgkmcnt(2)
	v_mfma_f32_32x32x16_bf16 v[48:63], v[136:139], v[84:87], v[48:63]
	s_cmp_lt_u32 s8, 4
	s_waitcnt lgkmcnt(1)
	v_mfma_f32_32x32x16_bf16 v[64:79], v[140:143], v[80:83], v[0:15]
	ds_read_b128 v[136:139], v153 offset:64
	ds_read_b128 v[140:143], v153 offset:96
	s_waitcnt lgkmcnt(2)
	v_mfma_f32_32x32x16_bf16 v[64:79], v[182:185], v[84:87], v[64:79]
	s_waitcnt lgkmcnt(1)
	v_mfma_f32_32x32x16_bf16 v[48:63], v[136:139], v[96:99], v[48:63]
	ds_read_b128 v[136:139], v153 offset:4672
	ds_read_b128 v[182:185], v153 offset:4704
	s_waitcnt lgkmcnt(1)
	v_mfma_f32_32x32x16_bf16 v[64:79], v[136:139], v[96:99], v[64:79]
	v_mfma_f32_32x32x16_bf16 v[48:63], v[140:143], v[100:103], v[48:63]
	s_waitcnt lgkmcnt(0)
	v_mfma_f32_32x32x16_bf16 v[64:79], v[182:185], v[100:103], v[64:79]
	s_setprio 0
	s_mul_i32 s33, s62, 0x2200
	v_add_u32_e32 v224, s33, v174
	v_add_u32_e32 v225, 0x5800, v224
	v_add_u32_e32 v224, 0x4800, v224
	ds_read2_b64 v[192:195], v224 offset1:2
	ds_read2_b64 v[196:199], v224 offset0:4 offset1:6
	ds_read2_b64 v[200:203], v224 offset0:8 offset1:10
	ds_read2_b64 v[204:207], v224 offset0:12 offset1:14
	ds_read2_b64 v[208:211], v225 offset0:32 offset1:34
	ds_read2_b64 v[212:215], v225 offset0:36 offset1:38
	ds_read2_b64 v[216:219], v225 offset0:40 offset1:42
	ds_read2_b64 v[220:223], v225 offset0:44 offset1:46
	s_cbranch_scc1 .LBB0_514
	s_add_i32 s63, s57, s25
	s_add_i32 s63, s63, 1
	s_cmp_lt_i32 s63, 8
	s_cbranch_scc1 .LBB0_510
	s_cmp_eq_u32 s63, 8
	s_cselect_b64 s[38:39], -1, 0
	s_cbranch_execz .LBB0_511
	s_branch .LBB0_512

;     ...
;             if (resc) { _Pragma("unroll") for (int r = 0; r < 16; ++r) { o0[r] *= fres; o1[r] *= fres; } }
.LBB0_517:
	s_andn2_b64 vcc, exec, s[38:39]
	s_waitcnt lgkmcnt(0)
	s_setprio 1
	v_mfma_f32_32x32x16_bf16 v[16:31], v[192:195], v[132:135], v[16:31]
	v_mfma_f32_32x32x16_bf16 v[32:47], v[208:211], v[132:135], v[32:47]
	v_mfma_f32_32x32x16_bf16 v[16:31], v[196:199], v[128:131], v[16:31]
	v_mfma_f32_32x32x16_bf16 v[32:47], v[212:215], v[128:131], v[32:47]
	v_mfma_f32_32x32x16_bf16 v[16:31], v[200:203], v[124:127], v[16:31]
	v_mfma_f32_32x32x16_bf16 v[32:47], v[216:219], v[124:127], v[32:47]
	v_mfma_f32_32x32x16_bf16 v[16:31], v[204:207], v[120:123], v[16:31]
	v_mfma_f32_32x32x16_bf16 v[32:47], v[220:223], v[120:123], v[32:47]
	s_setprio 0
	s_cbranch_vccnz .LBB0_519
	s_nop 11
	v_pk_mul_f32 v[30:31], v[136:137], v[30:31] op_sel_hi:[0,1]
	v_pk_mul_f32 v[28:29], v[136:137], v[28:29] op_sel_hi:[0,1]
	v_pk_mul_f32 v[26:27], v[136:137], v[26:27] op_sel_hi:[0,1]
	v_pk_mul_f32 v[24:25], v[136:137], v[24:25] op_sel_hi:[0,1]
	v_pk_mul_f32 v[22:23], v[136:137], v[22:23] op_sel_hi:[0,1]
	v_pk_mul_f32 v[20:21], v[136:137], v[20:21] op_sel_hi:[0,1]
	v_pk_mul_f32 v[18:19], v[136:137], v[18:19] op_sel_hi:[0,1]
	v_pk_mul_f32 v[16:17], v[136:137], v[16:17] op_sel_hi:[0,1]
	s_nop 2
	v_pk_mul_f32 v[46:47], v[136:137], v[46:47] op_sel_hi:[0,1]
	v_pk_mul_f32 v[44:45], v[136:137], v[44:45] op_sel_hi:[0,1]
	v_pk_mul_f32 v[42:43], v[136:137], v[42:43] op_sel_hi:[0,1]
	v_pk_mul_f32 v[40:41], v[136:137], v[40:41] op_sel_hi:[0,1]
	v_pk_mul_f32 v[38:39], v[136:137], v[38:39] op_sel_hi:[0,1]
	v_pk_mul_f32 v[36:37], v[136:137], v[36:37] op_sel_hi:[0,1]
	v_pk_mul_f32 v[34:35], v[136:137], v[34:35] op_sel_hi:[0,1]
	v_pk_mul_f32 v[32:33], v[136:137], v[32:33] op_sel_hi:[0,1]
